# cb_reduce: 32 partial-sum loads issued together, summed in the original order
# speedup vs baseline: 1.0070x; 1.0034x over previous
; __device__ __forceinline__ void cb_reduce(const Ctx& C, int l) {
;     const int e = C.gw * 64 + C.lane;
;     if (e < 512) { const int kv = e >> 8, n = e & 255; const float* pp = (const float*)(C.ws + WS_CBP) + (size_t)l * 64 * 256 + (size_t)kv * 32 * 256 + n;
;         float s = (kv ? INF(18, l, 256) : INF(15, l, 256))[n];
;         for (int ch = 0; ch < 32; ++ch) s += pp[ch * 256];
;         ((float*)(C.ws + WS_CB))[l * 512 + e] = s; }
; }
.LBB0_348:
	s_lshl_b32 s2, s8, 6
	v_or_b32_e32 v4, s2, v140
	v_cmp_gt_i32_e32 vcc, s65, v4
	s_and_saveexec_b64 s[0:1], vcc
	s_cbranch_execz .LBB0_350
	v_readlane_b32 s10, v254, 45
	v_readlane_b32 s11, v254, 46
	s_mov_b32 s11, s7
	s_ashr_i32 s4, s8, 2
	s_lshl_b64 s[8:9], s[10:11], 16
	s_add_u32 s3, s36, s8
	s_addc_u32 s6, s37, s9
	s_ashr_i32 s5, s4, 31
	s_lshl_b64 s[4:5], s[4:5], 15
	s_add_u32 s4, s3, s4
	v_mov_b32_e32 v0, 2
	s_addc_u32 s5, s6, s5
	v_lshlrev_b32_sdwa v0, v0, v4 dst_sel:DWORD dst_unused:UNUSED_PAD src0_sel:DWORD src1_sel:BYTE_0
	v_readlane_b32 s16, v253, 14
	v_lshl_add_u64 v[2:3], s[4:5], 0, v[0:1]
	s_mov_b64 s[4:5], 0x3902000
	v_readlane_b32 s17, v253, 15
	v_readlane_b32 s18, v253, 16
	v_readlane_b32 s19, v253, 17
	v_readlane_b32 s20, v253, 18
	v_readlane_b32 s21, v253, 19
	v_readlane_b32 s22, v253, 20
	v_readlane_b32 s23, v253, 21
	v_readlane_b32 s24, v253, 22
	v_readlane_b32 s25, v253, 23
	v_readlane_b32 s26, v253, 24
	v_readlane_b32 s27, v253, 25
	v_lshl_add_u64 v[6:7], v[2:3], 0, s[4:5]
	s_lshl_b64 s[4:5], s[10:11], 10
	v_readlane_b32 s28, v253, 26
	v_readlane_b32 s29, v253, 27
	v_readlane_b32 s30, v253, 28
	v_readlane_b32 s31, v253, 29
	s_mov_b64 s[16:17], s[20:21]
	v_readlane_b32 s72, v253, 30
	s_cmpk_lt_u32 s2, 0x100
	s_mov_b64 s[18:19], s[22:23]
	s_mov_b64 s[20:21], s[24:25]
	s_mov_b64 s[22:23], s[26:27]
	s_mov_b64 s[24:25], s[28:29]
	s_mov_b64 s[26:27], s[30:31]
	v_readlane_b32 s76, v253, 34
	v_readlane_b32 s77, v253, 35
	s_cselect_b32 s2, s26, s76
	s_cselect_b32 s3, s27, s77
	s_add_u32 s2, s2, s4
	s_addc_u32 s3, s3, s5
	global_load_dword v0, v0, s[2:3]
	s_mov_b32 s2, 0x3903000
	v_add_co_u32_e32 v8, vcc, s2, v2
	s_mov_b32 s2, 0x3904000
	s_nop 0
	v_addc_co_u32_e32 v9, vcc, 0, v3, vcc
	global_load_dword v10, v[8:9], off offset:-4096
	v_readlane_b32 s84, v253, 42
	v_readlane_b32 s85, v253, 43
	v_readlane_b32 s21, v254, 58
	v_readlane_b32 s20, v254, 57
	v_readlane_b32 s85, v254, 61
	v_readlane_b32 s84, v254, 60
	v_readlane_b32 s27, v254, 59
	v_readlane_b32 s26, v254, 56
	s_movk_i32 s49, 0x161
	v_readlane_b32 s73, v253, 31
	v_readlane_b32 s74, v253, 32
	v_readlane_b32 s75, v253, 33
	v_readlane_b32 s78, v253, 36
	v_readlane_b32 s79, v253, 37
	v_readlane_b32 s80, v253, 38
	v_readlane_b32 s81, v253, 39
	v_readlane_b32 s82, v253, 40
	v_readlane_b32 s83, v253, 41
	v_readlane_b32 s86, v253, 44
	v_readlane_b32 s87, v253, 45
	global_load_dword v11, v[6:7], off offset:1024
	global_load_dword v12, v[6:7], off offset:2048
	global_load_dword v13, v[6:7], off offset:3072
	v_add_co_u32_e32 v6, vcc, s2, v2
	s_mov_b32 s2, 0x3905000
	s_nop 0
	v_addc_co_u32_e32 v7, vcc, 0, v3, vcc
	global_load_dword v14, v[8:9], off
	global_load_dword v15, v[8:9], off offset:1024
	global_load_dword v16, v[8:9], off offset:2048
	global_load_dword v17, v[8:9], off offset:3072
	v_add_co_u32_e32 v8, vcc, s2, v2
	s_mov_b32 s2, 0x3906000
	s_nop 0
	v_addc_co_u32_e32 v9, vcc, 0, v3, vcc
	global_load_dword v18, v[8:9], off offset:-4096
	global_load_dword v19, v[6:7], off offset:1024
	global_load_dword v20, v[6:7], off offset:2048
	global_load_dword v21, v[6:7], off offset:3072
	v_add_co_u32_e32 v6, vcc, s2, v2
	s_mov_b32 s2, 0x3907000
	s_nop 0
	v_addc_co_u32_e32 v7, vcc, 0, v3, vcc
	global_load_dword v22, v[8:9], off
	global_load_dword v23, v[8:9], off offset:1024
	global_load_dword v24, v[8:9], off offset:2048
	global_load_dword v25, v[8:9], off offset:3072
	v_add_co_u32_e32 v8, vcc, s2, v2
	s_mov_b32 s2, 0x3908000
	s_nop 0
	v_addc_co_u32_e32 v9, vcc, 0, v3, vcc
	global_load_dword v26, v[8:9], off offset:-4096
	global_load_dword v27, v[6:7], off offset:1024
	global_load_dword v28, v[6:7], off offset:2048
	global_load_dword v29, v[6:7], off offset:3072
	v_add_co_u32_e32 v6, vcc, s2, v2
	s_mov_b32 s2, 0x3909000
	s_nop 0
	v_addc_co_u32_e32 v7, vcc, 0, v3, vcc
	v_add_co_u32_e32 v2, vcc, s2, v2
	s_mov_b32 s2, s10
	s_nop 0
	v_addc_co_u32_e32 v3, vcc, 0, v3, vcc
	v_writelane_b32 v254, s2, 45
	global_load_dword v30, v[8:9], off
	v_writelane_b32 v254, s3, 46
	global_load_dword v31, v[8:9], off offset:1024
	global_load_dword v32, v[8:9], off offset:2048
	global_load_dword v33, v[8:9], off offset:3072
	global_load_dword v34, v[2:3], off offset:-4096
	global_load_dword v35, v[6:7], off offset:1024
	global_load_dword v36, v[6:7], off offset:2048
	global_load_dword v37, v[6:7], off offset:3072
	global_load_dword v38, v[2:3], off
	global_load_dword v39, v[2:3], off offset:1024
	global_load_dword v40, v[2:3], off offset:2048
	global_load_dword v41, v[2:3], off offset:3072
	s_waitcnt vmcnt(0)
	v_add_f32_e32 v0, v0, v10
	v_add_f32_e32 v0, v0, v11
	v_add_f32_e32 v0, v0, v12
	v_add_f32_e32 v0, v0, v13
	v_add_f32_e32 v0, v0, v14
	v_add_f32_e32 v0, v0, v15
	v_add_f32_e32 v0, v0, v16
	v_add_f32_e32 v0, v0, v17
	v_add_f32_e32 v0, v0, v18
	v_add_f32_e32 v0, v0, v19
	v_add_f32_e32 v0, v0, v20
	v_add_f32_e32 v0, v0, v21
	v_add_f32_e32 v0, v0, v22
	v_add_f32_e32 v0, v0, v23
	v_add_f32_e32 v0, v0, v24
	v_add_f32_e32 v0, v0, v25
	v_add_f32_e32 v0, v0, v26
	v_add_f32_e32 v0, v0, v27
	v_add_f32_e32 v0, v0, v28
	v_add_f32_e32 v0, v0, v29
	v_add_f32_e32 v0, v0, v30
	v_add_f32_e32 v0, v0, v31
	v_add_f32_e32 v0, v0, v32
	v_add_f32_e32 v0, v0, v33
	v_add_f32_e32 v0, v0, v34
	v_add_f32_e32 v0, v0, v35
	v_add_f32_e32 v0, v0, v36
	v_add_f32_e32 v0, v0, v37
	v_add_f32_e32 v0, v0, v38
	v_add_f32_e32 v0, v0, v39
	v_add_f32_e32 v0, v0, v40
	v_add_f32_e32 v0, v0, v41
	v_lshl_add_u32 v2, s10, 9, v4
	v_ashrrev_i32_e32 v3, 31, v2
	v_lshl_add_u64 v[2:3], v[2:3], 2, s[36:37]
	v_add_co_u32_e32 v2, vcc, 0x3900000, v2
	s_nop 1
	v_addc_co_u32_e32 v3, vcc, 0, v3, vcc
	global_store_dword v[2:3], v0, off
